# phase 3 (compress stage 2): 4 rows per wave accumulated in one software-pipelined f32 fmac loop (same per-row c order), instead of 4 serial latency-bound loops
# speedup vs baseline: 1.2600x; 1.0064x over previous
; #define LAS __attribute__((address_space(3)))
; __device__ __forceinline__ void phase3(const Args& a, LAS unsigned char* lds) {
;     ...
; #pragma unroll 1
;         for (int rr = 0; rr < 4; ++rr) {
;             const int R = item * 32 + wave * 4 + rr, bh = (R >> 7) & 31, n = R & 127;
;             f32x4 h4 = *(const LAS f32x4*)(c1s + 4 * lane);
; #pragma unroll
;             for (int kc = 0; kc < 4; ++kc) h4 += *(const f32x4*)(part + ((size_t)kc * 8192 + R) * 256 + 4 * lane);
;             h4.x = gelu_tanh(h4.x); h4.y = gelu_tanh(h4.y); h4.z = gelu_tanh(h4.z); h4.w = gelu_tanh(h4.w);
;             *(LAS f32x4*)(hids + wave * 256 + 4 * lane) = h4;
;             asm volatile("s_waitcnt lgkmcnt(0)" ::: "memory");
;             float acc = 0.f;
; #pragma unroll 8
;             for (int c = 0; c < 256; ++c) acc += hids[wave * 256 + c] * w2s[c * 64 + lane];
.LBB0_591:
	s_or_b64 exec, exec, s[0:1]
	v_lshl_add_u32 v23, s20, 5, v13
	s_cmpk_gt_u32 s20, 0x7f
	v_lshlrev_b32_e32 v2, 6, v23
	s_cselect_b64 s[12:13], -1, 0
	v_and_or_b32 v24, v2, s17, v17
	v_and_b32_e32 v25, 0xf80, v23
	s_mov_b32 s21, 0
	v_lshl_add_u32 v56, v15, 1, v15
	v_add_u32_e32 v56, v56, v16
	v_add_u32_e32 v56, 0x2000, v56
	v_lshlrev_b32_e32 v57, 2, v15
	v_add_u32_e32 v57, 0x12400, v57
	s_waitcnt lgkmcnt(0)
	s_barrier
	s_branch .LBB0_593
.LBB0_592:
	s_add_u32 s0, s78, s0
	s_addc_u32 s1, s79, s1
	s_add_i32 s21, s21, 1
	v_lshl_add_u64 v[10:11], v[2:3], 1, s[0:1]
	s_cmp_eq_u32 s21, 4
	global_store_short_d16_hi v[10:11], v26, off
	s_cbranch_scc1 .LBB0_588
	s_branch .Lp3_rowc
.LBB0_593:
	v_or_b32_e32 v10, s21, v23
	v_ashrrev_i32_e32 v11, 31, v10
	v_lshlrev_b64 v[26:27], 10, v[10:11]
	v_lshl_add_u64 v[38:39], v[4:5], 0, v[26:27]
	v_add_co_u32_e32 v34, vcc, 0x800000, v38
	s_nop 1
	v_addc_co_u32_e32 v35, vcc, 0, v39, vcc
	global_load_dwordx4 v[26:29], v[38:39], off
	global_load_dwordx4 v[30:33], v[34:35], off
	v_add_co_u32_e32 v34, vcc, 0x1000000, v38
	ds_read_b128 v[42:45], v14
	s_nop 0
	v_addc_co_u32_e32 v35, vcc, 0, v39, vcc
	v_add_co_u32_e32 v38, vcc, 0x1800000, v38
	global_load_dwordx4 v[34:37], v[34:35], off
	s_nop 0
	v_addc_co_u32_e32 v39, vcc, 0, v39, vcc
	global_load_dwordx4 v[38:41], v[38:39], off
	s_waitcnt vmcnt(3) lgkmcnt(0)
	v_pk_add_f32 v[28:29], v[44:45], v[28:29]
	s_waitcnt vmcnt(2)
	v_pk_add_f32 v[28:29], v[28:29], v[32:33]
	v_pk_add_f32 v[26:27], v[42:43], v[26:27]
	s_waitcnt vmcnt(1)
	v_pk_add_f32 v[28:29], v[28:29], v[36:37]
	v_pk_add_f32 v[26:27], v[26:27], v[30:31]
	s_waitcnt vmcnt(0)
	v_pk_add_f32 v[28:29], v[28:29], v[40:41]
	v_pk_add_f32 v[26:27], v[26:27], v[34:35]
	v_mul_f32_e32 v30, 0x3d372713, v28
	v_mul_f32_e32 v31, 0x3d372713, v29
	v_pk_add_f32 v[26:27], v[26:27], v[38:39]
	v_mul_f32_e32 v30, v28, v30
	v_mul_f32_e32 v31, v29, v31
	v_mul_f32_e32 v2, 0x3d372713, v26
	v_mul_f32_e32 v11, 0x3d372713, v27
	v_fma_f32 v30, v28, v30, v28
	v_fma_f32 v31, v29, v31, v29
	v_mul_f32_e32 v2, v26, v2
	v_mul_f32_e32 v11, v27, v11
	v_mul_f32_e32 v30, 0x3f4c422a, v30
	v_mul_f32_e32 v31, 0x3f4c422a, v31
	v_fma_f32 v2, v26, v2, v26
	v_fma_f32 v11, v27, v11, v27
	v_mul_f32_e32 v30, -2.0, v30
	v_mul_f32_e32 v31, -2.0, v31
	v_mul_f32_e32 v2, 0x3f4c422a, v2
	v_mul_f32_e32 v11, 0x3f4c422a, v11
	v_mul_f32_e32 v32, 0x3fb8aa3b, v30
	v_mul_f32_e32 v31, 0x3fb8aa3b, v31
	v_mul_f32_e32 v2, -2.0, v2
	v_mul_f32_e32 v11, -2.0, v11
	v_exp_f32_e32 v32, v32
	v_exp_f32_e32 v33, v31
	v_mul_f32_e32 v2, 0x3fb8aa3b, v2
	v_mul_f32_e32 v11, 0x3fb8aa3b, v11
	v_exp_f32_e32 v30, v2
	v_exp_f32_e32 v31, v11
	v_pk_add_f32 v[32:33], v[32:33], 1.0 op_sel_hi:[1,0]
	v_pk_add_f32 v[30:31], v[30:31], 1.0 op_sel_hi:[1,0]
	v_div_scale_f32 v2, s[0:1], v33, v33, v29
	v_div_scale_f32 v34, s[0:1], v32, v32, v28
	v_rcp_f32_e32 v40, v2
	v_div_scale_f32 v36, s[4:5], v31, v31, v27
	v_rcp_f32_e32 v41, v34
	v_div_scale_f32 v38, s[6:7], v30, v30, v26
	v_rcp_f32_e32 v42, v36
	v_rcp_f32_e32 v43, v38
	v_fma_f32 v44, -v2, v40, 1.0
	v_div_scale_f32 v11, vcc, v29, v33, v29
	v_fma_f32 v45, -v34, v41, 1.0
	v_fmac_f32_e32 v40, v44, v40
	v_div_scale_f32 v35, s[0:1], v28, v32, v28
	v_fma_f32 v46, -v36, v42, 1.0
	v_fmac_f32_e32 v41, v45, v41
	v_mul_f32_e32 v44, v11, v40
	v_div_scale_f32 v37, s[4:5], v27, v31, v27
	v_fma_f32 v47, -v38, v43, 1.0
	v_fmac_f32_e32 v42, v46, v42
	v_mul_f32_e32 v45, v35, v41
	v_fma_f32 v48, -v2, v44, v11
	v_div_scale_f32 v39, s[6:7], v26, v30, v26
	v_fmac_f32_e32 v43, v47, v43
	v_mul_f32_e32 v46, v37, v42
	v_fma_f32 v49, -v34, v45, v35
	v_fmac_f32_e32 v44, v48, v40
	v_mul_f32_e32 v47, v39, v43
	v_fma_f32 v50, -v36, v46, v37
	v_fmac_f32_e32 v45, v49, v41
	v_fma_f32 v2, -v2, v44, v11
	v_fma_f32 v51, -v38, v47, v39
	v_fmac_f32_e32 v46, v50, v42
	v_fma_f32 v11, -v34, v45, v35
	v_div_fmas_f32 v2, v2, v40, v44
	s_mov_b64 vcc, s[0:1]
	v_fmac_f32_e32 v47, v51, v43
	v_fma_f32 v34, -v36, v46, v37
	v_div_fixup_f32 v29, v2, v33, v29
	v_div_fmas_f32 v2, v11, v41, v45
	s_mov_b64 vcc, s[4:5]
	v_fma_f32 v35, -v38, v47, v39
	v_div_fixup_f32 v28, v2, v32, v28
	v_div_fmas_f32 v2, v34, v42, v46
	s_mov_b64 vcc, s[6:7]
	v_div_fixup_f32 v27, v2, v31, v27
	v_div_fmas_f32 v2, v35, v43, v47
	v_div_fixup_f32 v26, v2, v30, v26
	s_lshl_b32 s0, s21, 10
	v_add_u32_e32 v2, s0, v56
	ds_write_b128 v2, v[26:29]
	s_add_i32 s21, s21, 1
	s_cmp_lt_u32 s21, 4
	s_cbranch_scc1 .LBB0_593
	s_waitcnt lgkmcnt(0)
	v_mov_b32_e32 v60, 0
	v_mov_b32_e32 v61, 0
	v_mov_b32_e32 v62, 0
	v_mov_b32_e32 v63, 0
	v_mov_b32_e32 v58, v0
	v_mov_b32_e32 v59, v57
	s_movk_i32 s0, 16
	ds_read2st64_b32 v[64:65], v58 offset0:0 offset1:1
	ds_read2st64_b32 v[66:67], v58 offset0:2 offset1:3
	ds_read2st64_b32 v[68:69], v58 offset0:4 offset1:5
	ds_read2st64_b32 v[70:71], v58 offset0:6 offset1:7
	ds_read_b128 v[104:107], v59 offset:0
	ds_read_b128 v[108:111], v59 offset:16
	ds_read_b128 v[112:115], v59 offset:1024
	ds_read_b128 v[116:119], v59 offset:1040
	ds_read_b128 v[120:123], v59 offset:2048
	ds_read_b128 v[124:127], v59 offset:2064
	ds_read_b128 v[128:131], v59 offset:3072
	ds_read_b128 v[132:135], v59 offset:3088
; __device__ __forceinline__ unsigned f2bf(float f) { unsigned u = __float_as_uint(f); return (u + 0x7fffu + ((u >> 16) & 1u)) >> 16; }
; __device__ __forceinline__ void phase3(const Args& a, LAS unsigned char* lds) {
;     ...
;             float acc = 0.f;
; #pragma unroll 8
;             for (int c = 0; c < 256; ++c) acc += hids[wave * 256 + c] * w2s[c * 64 + lane];
;             if (kv == 0) {
;                 const float ss = wave_sum(acc * acc);
;                 const float y = acc * rsqrtf(ss * (1.f / 64.f) + EPS) * a.in[4][lane];
;                 kcmp[((size_t)bh * 128 + n) * 64 + lane] = (bf16_t)f2bf(n < 127 ? y : 0.f);
;             } else {
;                 vcmpT[((size_t)bh * 64 + lane) * 128 + n] = (bf16_t)f2bf(n < 127 ? acc : 0.f);
;             }
.Lp3_fma:
	ds_read2st64_b32 v[72:73], v58 offset0:8 offset1:9
	ds_read2st64_b32 v[74:75], v58 offset0:10 offset1:11
	ds_read2st64_b32 v[76:77], v58 offset0:12 offset1:13
	ds_read2st64_b32 v[78:79], v58 offset0:14 offset1:15
	ds_read_b128 v[200:203], v59 offset:32
	ds_read_b128 v[204:207], v59 offset:48
	ds_read_b128 v[208:211], v59 offset:1056
	ds_read_b128 v[212:215], v59 offset:1072
	ds_read_b128 v[216:219], v59 offset:2080
	ds_read_b128 v[220:223], v59 offset:2096
	ds_read_b128 v[224:227], v59 offset:3104
	ds_read_b128 v[228:231], v59 offset:3120
	s_waitcnt lgkmcnt(12)
	v_fmac_f32_e32 v60, v104, v64
	v_fmac_f32_e32 v61, v112, v64
	v_fmac_f32_e32 v62, v120, v64
	v_fmac_f32_e32 v63, v128, v64
	v_fmac_f32_e32 v60, v105, v65
	v_fmac_f32_e32 v61, v113, v65
	v_fmac_f32_e32 v62, v121, v65
	v_fmac_f32_e32 v63, v129, v65
	v_fmac_f32_e32 v60, v106, v66
	v_fmac_f32_e32 v61, v114, v66
	v_fmac_f32_e32 v62, v122, v66
	v_fmac_f32_e32 v63, v130, v66
	v_fmac_f32_e32 v60, v107, v67
	v_fmac_f32_e32 v61, v115, v67
	v_fmac_f32_e32 v62, v123, v67
	v_fmac_f32_e32 v63, v131, v67
	v_fmac_f32_e32 v60, v108, v68
	v_fmac_f32_e32 v61, v116, v68
	v_fmac_f32_e32 v62, v124, v68
	v_fmac_f32_e32 v63, v132, v68
	v_fmac_f32_e32 v60, v109, v69
	v_fmac_f32_e32 v61, v117, v69
	v_fmac_f32_e32 v62, v125, v69
	v_fmac_f32_e32 v63, v133, v69
	v_fmac_f32_e32 v60, v110, v70
	v_fmac_f32_e32 v61, v118, v70
	v_fmac_f32_e32 v62, v126, v70
	v_fmac_f32_e32 v63, v134, v70
	v_fmac_f32_e32 v60, v111, v71
	v_fmac_f32_e32 v61, v119, v71
	v_fmac_f32_e32 v62, v127, v71
	v_fmac_f32_e32 v63, v135, v71
	v_add_u32_e32 v58, 0x1000, v58
	v_add_u32_e32 v59, 64, v59
	s_add_i32 s0, s0, -1
	s_cmp_eq_u32 s0, 0
	s_cbranch_scc1 .Lp3_fma_tail
	ds_read2st64_b32 v[64:65], v58 offset0:0 offset1:1
	ds_read2st64_b32 v[66:67], v58 offset0:2 offset1:3
	ds_read2st64_b32 v[68:69], v58 offset0:4 offset1:5
	ds_read2st64_b32 v[70:71], v58 offset0:6 offset1:7
	ds_read_b128 v[104:107], v59 offset:0
	ds_read_b128 v[108:111], v59 offset:16
	ds_read_b128 v[112:115], v59 offset:1024
	ds_read_b128 v[116:119], v59 offset:1040
	ds_read_b128 v[120:123], v59 offset:2048
	ds_read_b128 v[124:127], v59 offset:2064
	ds_read_b128 v[128:131], v59 offset:3072
	ds_read_b128 v[132:135], v59 offset:3088
	s_waitcnt lgkmcnt(12)
	v_fmac_f32_e32 v60, v200, v72
	v_fmac_f32_e32 v61, v208, v72
	v_fmac_f32_e32 v62, v216, v72
	v_fmac_f32_e32 v63, v224, v72
	v_fmac_f32_e32 v60, v201, v73
	v_fmac_f32_e32 v61, v209, v73
	v_fmac_f32_e32 v62, v217, v73
	v_fmac_f32_e32 v63, v225, v73
	v_fmac_f32_e32 v60, v202, v74
	v_fmac_f32_e32 v61, v210, v74
	v_fmac_f32_e32 v62, v218, v74
	v_fmac_f32_e32 v63, v226, v74
	v_fmac_f32_e32 v60, v203, v75
	v_fmac_f32_e32 v61, v211, v75
	v_fmac_f32_e32 v62, v219, v75
	v_fmac_f32_e32 v63, v227, v75
	v_fmac_f32_e32 v60, v204, v76
	v_fmac_f32_e32 v61, v212, v76
	v_fmac_f32_e32 v62, v220, v76
	v_fmac_f32_e32 v63, v228, v76
	v_fmac_f32_e32 v60, v205, v77
	v_fmac_f32_e32 v61, v213, v77
	v_fmac_f32_e32 v62, v221, v77
	v_fmac_f32_e32 v63, v229, v77
	v_fmac_f32_e32 v60, v206, v78
	v_fmac_f32_e32 v61, v214, v78
	v_fmac_f32_e32 v62, v222, v78
	v_fmac_f32_e32 v63, v230, v78
	v_fmac_f32_e32 v60, v207, v79
	v_fmac_f32_e32 v61, v215, v79
	v_fmac_f32_e32 v62, v223, v79
	v_fmac_f32_e32 v63, v231, v79
	s_branch .Lp3_fma
.Lp3_fma_tail:
	s_waitcnt lgkmcnt(0)
	v_fmac_f32_e32 v60, v200, v72
	v_fmac_f32_e32 v61, v208, v72
	v_fmac_f32_e32 v62, v216, v72
	v_fmac_f32_e32 v63, v224, v72
	v_fmac_f32_e32 v60, v201, v73
	v_fmac_f32_e32 v61, v209, v73
	v_fmac_f32_e32 v62, v217, v73
	v_fmac_f32_e32 v63, v225, v73
	v_fmac_f32_e32 v60, v202, v74
	v_fmac_f32_e32 v61, v210, v74
	v_fmac_f32_e32 v62, v218, v74
	v_fmac_f32_e32 v63, v226, v74
	v_fmac_f32_e32 v60, v203, v75
	v_fmac_f32_e32 v61, v211, v75
	v_fmac_f32_e32 v62, v219, v75
	v_fmac_f32_e32 v63, v227, v75
	v_fmac_f32_e32 v60, v204, v76
	v_fmac_f32_e32 v61, v212, v76
	v_fmac_f32_e32 v62, v220, v76
	v_fmac_f32_e32 v63, v228, v76
	v_fmac_f32_e32 v60, v205, v77
	v_fmac_f32_e32 v61, v213, v77
	v_fmac_f32_e32 v62, v221, v77
	v_fmac_f32_e32 v63, v229, v77
	v_fmac_f32_e32 v60, v206, v78
	v_fmac_f32_e32 v61, v214, v78
	v_fmac_f32_e32 v62, v222, v78
	v_fmac_f32_e32 v63, v230, v78
	v_fmac_f32_e32 v60, v207, v79
	v_fmac_f32_e32 v61, v215, v79
	v_fmac_f32_e32 v62, v223, v79
	v_fmac_f32_e32 v63, v231, v79
	s_mov_b32 s21, 0
.Lp3_rowc:
	v_or_b32_e32 v10, s21, v23
	v_mov_b32_e32 v11, v60
	s_cmp_eq_u32 s21, 0
	s_cbranch_scc1 .Lp3_sel
	v_mov_b32_e32 v11, v61
	s_cmp_eq_u32 s21, 1
	s_cbranch_scc1 .Lp3_sel
	v_mov_b32_e32 v11, v62
	s_cmp_eq_u32 s21, 2
	s_cbranch_scc1 .Lp3_sel
	v_mov_b32_e32 v11, v63
.Lp3_sel:
	v_and_b32_e32 v10, 0x7f, v10
	s_mov_b64 s[4:5], -1
	s_and_b64 vcc, exec, s[12:13]
	v_cmp_ne_u32_e64 s[0:1], s16, v10
	s_cbranch_vccz .LBB0_597
	s_nop 0
	v_cndmask_b32_e64 v2, 0, v11, s[0:1]
	v_bfe_u32 v26, v2, 16, 1
	v_add3_u32 v26, v2, v26, s19
	v_or_b32_e32 v2, v10, v24
	s_mov_b64 s[4:5], 0
